# attention + gMLP: one static s_setprio 1 for waves 0-3 for the whole phase (reset at the gMLP end), on top of the previous best
# baseline (speedup 1.0000x reference)
; #define FRESH_IDS() int wave = wave_k; asm volatile("" : "+s"(wave)); const int lane = pg8::fresh_lane(); const int tid = wave * 64 + lane; const int gw = bx * NWAVES + wave; (void)gw; (void)tid
; __device__ __forceinline__ void attn_load(AttnPre& P, const bf16* Z, const AttnUid& u, int tid, int wave, int lane) {
;     const int b = u.bh >> 3, h = u.bh & 7;
;     const bf16* Zb = Z + (size_t)b * SEQ * INW;
; #pragma unroll
;     for (int i = 0; i < 8; ++i) {
;         const int c = tid + 512 * i, j = c >> 4, ch = c & 15;
;         const int I = (u.n - 1) * 128 + j;
;         if (i < 4 && u.reuse) continue;
;         if (I >= 0) { const bf16* p = Zb + (size_t)(I * u.d + u.r) * INW + h * HD + ch * 8; P.k[i] = *(const v4u*)p; P.v[i] = *(const v4u*)(p + 1024); }
;         else { P.k[i] = (v4u){0u, 0u, 0u, 0u}; P.v[i] = P.k[i]; }
;     }
; __global__ void __launch_bounds__(NWAVES * 64, 2) hybrid_fwd(Args a) {
;     ...
;             FRESH_IDS();
;             const int vx = bx & 7, vr = bx >> 3;
;             AttnPre P; AttnUid cu = attn_decode_chain(vx, vr, 0);
;             attn_load(P, Z, cu, tid, wave, lane);
.LBB0_203:
	s_or_b64 exec, exec, s[0:1]
	v_readlane_b32 s0, v252, 13
	v_readlane_b32 s1, v252, 14
	v_readlane_b32 s2, v252, 15
	v_readlane_b32 s3, v252, 16
	v_readlane_b32 s4, v252, 37
	s_mov_b64 s[0:1], s[2:3]
	s_waitcnt lgkmcnt(0)
	s_barrier
	s_cselect_b32 s101, 1, 0
	v_readlane_b32 s100, v252, 37
	s_cmp_ge_u32 s100, 4
	s_cbranch_scc1 .Lprio_attn
	s_setprio 1
.Lprio_attn:
	s_cmp_lg_u32 s101, 0
	v_mbcnt_lo_u32_b32 v70, -1, 0
	v_mbcnt_hi_u32_b32 v70, -1, v70
	v_readlane_b32 s2, v252, 63
	s_add_u32 s0, s0, s2
	v_readlane_b32 s2, v252, 62
	s_addc_u32 s1, s1, s2
	v_lshl_add_u32 v60, s4, 6, v70
	s_add_u32 s0, s0, 0xf800000
	v_readlane_b32 s2, v252, 46
	s_addc_u32 s1, s1, 0
	s_lshl_b32 s56, s2, 1
	v_lshlrev_b32_e32 v71, 3, v70
	v_ashrrev_i32_e32 v136, 4, v60
	s_add_u32 s2, s0, s56
	v_and_b32_e32 v1, 0x78, v71
	v_add_u32_e32 v137, 0xffffff80, v136
	v_mov_b32_e32 v6, v0
	v_mov_b32_e32 v7, v0
	s_addc_u32 s3, s1, 0
	v_lshlrev_b32_e32 v128, 1, v1
	v_mov_b32_e32 v129, v0
	v_add_u32_e32 v1, s58, v137
	v_mov_b32_e32 v4, v0
	v_mov_b32_e32 v5, v0
	v_mov_b64_e32 v[10:11], v[6:7]
	v_mov_b64_e32 v[14:15], v[6:7]
	v_lshl_add_u64 v[68:69], s[2:3], 0, v[128:129]
	v_cmp_lt_i32_e32 vcc, -1, v1
	v_mov_b64_e32 v[8:9], v[4:5]
	v_mov_b64_e32 v[12:13], v[4:5]
	s_and_saveexec_b64 s[2:3], vcc
	s_cbranch_execz .LBB0_205
	v_lshlrev_b32_e32 v1, s53, v1
	v_add_u32_e32 v1, s55, v1
	v_mad_u64_u32 v[2:3], s[6:7], v1, s59, v[68:69]
	global_load_dwordx4 v[8:11], v[2:3], off
	global_load_dwordx4 v[12:15], v[2:3], off offset:2048

; __device__ __forceinline__ int fresh_lane() { int l; asm volatile("v_mbcnt_lo_u32_b32 %0, -1, 0\n\tv_mbcnt_hi_u32_b32 %0, -1, %0" : "=v"(l)); return l; }
; __device__ __forceinline__ void xcd_barrier(const XcdBarrier& b, const int wave) {
;     const bool leader = wave == 0 && pg8::fresh_lane() == 0;
;     asm volatile("s_waitcnt vmcnt(0)" ::: "memory");
;     __syncthreads();
;     if (leader) {
; __global__ void __launch_bounds__(NWAVES * 64, 2) hybrid_fwd(Args a) {
;     ...
;         xcd_barrier(bar, wave_k);
.LBB0_275:
	s_setprio 0
	v_readlane_b32 s0, v251, 49
	v_readlane_b32 s1, v251, 50
	s_and_b64 vcc, exec, s[0:1]
	s_mov_b64 s[2:3], 0
	s_movk_i32 s54, 0xa1
	v_readlane_b32 s13, v251, 18
	v_readlane_b32 s23, v251, 20
	s_movk_i32 s56, 0x300
	s_mov_b64 s[24:25], 0x20000
	s_mov_b64 s[26:27], 0x40000
	s_cbranch_vccnz .LBB0_277
	v_mbcnt_lo_u32_b32 v1, -1, 0
	v_mbcnt_hi_u32_b32 v1, -1, v1
	s_nop 0
	v_cmp_eq_u32_e32 vcc, 0, v1
	s_and_b64 s[2:3], vcc, exec
